# all four RMSNorm instances (norm1 pre-loop, norm2, norm1 next layer, final) use the hand-written pipelined row loop
# speedup vs baseline: 1.0245x; 1.0116x over previous
.LBB0_297:
	s_or_b64 exec, exec, s[0:1]
	v_readlane_b32 s12, v254, 0
	v_readlane_b32 s13, v254, 1
	v_readlane_b32 s14, v254, 2
	v_readlane_b32 s15, v254, 3
	v_readlane_b32 s24, v254, 12
	v_readlane_b32 s25, v254, 13
	v_readlane_b32 s26, v254, 14
	v_readlane_b32 s27, v254, 15
	s_mov_b64 s[12:13], s[24:25]
	s_mov_b64 s[14:15], s[26:27]
	s_add_u32 s64, s14, 0x50ae500
	v_mov_b32_e32 v0, v222
	s_addc_u32 s65, s15, 0
	s_barrier
	s_lshl_b32 s0, s2, 3
	v_ashrrev_i32_e32 v1, 6, v0
	v_readlane_b32 s16, v254, 4
	v_readlane_b32 s17, v254, 5
	v_readlane_b32 s18, v254, 6
	v_readlane_b32 s19, v254, 7
	v_readlane_b32 s20, v254, 8
	v_readlane_b32 s21, v254, 9
	v_readlane_b32 s22, v254, 10
	v_readlane_b32 s23, v254, 11
	v_writelane_b32 v254, s0, 57
	v_add_u32_e32 v4, s0, v1
	s_mov_b32 s0, 0x9000
	v_cmp_gt_i32_e32 vcc, s0, v4
	v_mbcnt_lo_u32_b32 v26, -1, 0
	s_and_saveexec_b64 s[0:1], vcc
	s_cbranch_execz .LBB0_304
	s_lshl_b32 s3, s95, 3
	s_mov_b64 s[18:19], s[10:11]
	v_readfirstlane_b32 s7, v4
	v_mbcnt_lo_u32_b32 v10, -1, 0
	v_mbcnt_hi_u32_b32 v10, -1, v10
	v_lshlrev_b32_e32 v2, 4, v10
	v_lshlrev_b32_e32 v3, 3, v10
	v_xor_b32_e32 v4, 32, v10
	v_lshlrev_b32_e32 v4, 2, v4
	v_xor_b32_e32 v5, 16, v10
	v_lshlrev_b32_e32 v5, 2, v5
	v_xor_b32_e32 v6, 8, v10
	v_lshlrev_b32_e32 v6, 2, v6
	v_xor_b32_e32 v7, 4, v10
	v_lshlrev_b32_e32 v7, 2, v7
	v_xor_b32_e32 v8, 2, v10
	v_lshlrev_b32_e32 v8, 2, v8
	v_xor_b32_e32 v9, 1, v10
	v_lshlrev_b32_e32 v9, 2, v9
	v_mov_b32_e32 v16, 0x358637bd
	v_readlane_b32 s22, v254, 37
	v_readlane_b32 s23, v254, 38
	v_readlane_b32 s24, v254, 41
	v_readlane_b32 s25, v254, 42
	v_readlane_b32 s20, v254, 14
	v_readlane_b32 s21, v254, 15
	s_nop 4
	global_load_dwordx4 v[136:139], v2, s[18:19] offset:0
	global_load_dwordx4 v[140:143], v2, s[18:19] offset:1024
	global_load_dwordx4 v[144:147], v2, s[18:19] offset:2048
	global_load_dwordx4 v[148:151], v2, s[18:19] offset:3072
	s_cmp_lt_u32 s7, 0x8000
	s_cselect_b32 s10, s22, s24
	s_cselect_b32 s11, s23, s25
	s_cselect_b32 s5, s7, 0x8000
	s_and_b32 s26, s7, 0x7fff
	s_lshl_b32 s27, s26, 12
	s_lshr_b32 s26, s26, 20
	s_add_u32 s10, s10, s27
	s_addc_u32 s11, s11, s26
	s_lshr_b32 s5, s5, 11
	s_mul_i32 s5, s5, 0x6000
	s_add_u32 s14, s20, s5
	s_addc_u32 s15, s21, 0
	s_add_u32 s16, s14, 0x0
	s_addc_u32 s17, s15, 0
	s_add_u32 s14, s14, 0x1000
	s_addc_u32 s15, s15, 0
	global_load_dwordx4 v[40:43], v2, s[10:11] offset:0
	global_load_dwordx4 v[44:47], v2, s[10:11] offset:1024
	global_load_dwordx4 v[48:51], v2, s[10:11] offset:2048
	global_load_dwordx4 v[52:55], v2, s[10:11] offset:3072
	global_load_dwordx4 v[56:59], v2, s[14:15] offset:0
	global_load_dwordx4 v[60:63], v2, s[14:15] offset:1024
	global_load_dwordx4 v[64:67], v2, s[14:15] offset:2048
	global_load_dwordx4 v[68:71], v2, s[14:15] offset:3072
	global_load_dwordx4 v[72:75], v2, s[16:17] offset:0
	global_load_dwordx4 v[76:79], v2, s[16:17] offset:1024
	global_load_dwordx4 v[80:83], v2, s[16:17] offset:2048
	global_load_dwordx4 v[84:87], v2, s[16:17] offset:3072
	s_waitcnt vmcnt(0)
.Ln1p_loop:
	s_add_i32 s4, s7, s3
	s_cmp_lt_i32 s4, 0x9000
	s_cbranch_scc0 .Ln1p_last0
	s_cmp_lt_u32 s4, 0x8000
	s_cselect_b32 s10, s22, s24
	s_cselect_b32 s11, s23, s25
	s_cselect_b32 s5, s4, 0x8000
	s_and_b32 s26, s4, 0x7fff
	s_lshl_b32 s27, s26, 12
	s_lshr_b32 s26, s26, 20
	s_add_u32 s10, s10, s27
	s_addc_u32 s11, s11, s26
	s_lshr_b32 s5, s5, 11
	s_mul_i32 s5, s5, 0x6000
	s_add_u32 s14, s20, s5
	s_addc_u32 s15, s21, 0
	s_add_u32 s16, s14, 0x0
	s_addc_u32 s17, s15, 0
	s_add_u32 s14, s14, 0x1000
	s_addc_u32 s15, s15, 0
	global_load_dwordx4 v[88:91], v2, s[10:11] offset:0
	global_load_dwordx4 v[92:95], v2, s[10:11] offset:1024
	global_load_dwordx4 v[96:99], v2, s[10:11] offset:2048
	global_load_dwordx4 v[100:103], v2, s[10:11] offset:3072
	global_load_dwordx4 v[104:107], v2, s[14:15] offset:0
	global_load_dwordx4 v[108:111], v2, s[14:15] offset:1024
	global_load_dwordx4 v[112:115], v2, s[14:15] offset:2048
	global_load_dwordx4 v[116:119], v2, s[14:15] offset:3072
	global_load_dwordx4 v[120:123], v2, s[16:17] offset:0
	global_load_dwordx4 v[124:127], v2, s[16:17] offset:1024
	global_load_dwordx4 v[128:131], v2, s[16:17] offset:2048
	global_load_dwordx4 v[132:135], v2, s[16:17] offset:3072
	v_mul_f32_e32 v12, v40, v40
	v_fmac_f32_e32 v12, v41, v41
	v_fmac_f32_e32 v12, v42, v42
	v_fmac_f32_e32 v12, v43, v43
	v_fmac_f32_e32 v12, v44, v44
	v_fmac_f32_e32 v12, v45, v45
	v_fmac_f32_e32 v12, v46, v46
	v_fmac_f32_e32 v12, v47, v47
	v_fmac_f32_e32 v12, v48, v48
	v_fmac_f32_e32 v12, v49, v49
	v_fmac_f32_e32 v12, v50, v50
	v_fmac_f32_e32 v12, v51, v51
	v_fmac_f32_e32 v12, v52, v52
	v_fmac_f32_e32 v12, v53, v53
	v_fmac_f32_e32 v12, v54, v54
	v_fmac_f32_e32 v12, v55, v55
	ds_bpermute_b32 v13, v4, v12
	s_waitcnt lgkmcnt(0)
	v_add_f32_e32 v12, v12, v13
	ds_bpermute_b32 v13, v5, v12
	s_waitcnt lgkmcnt(0)
	v_add_f32_e32 v12, v12, v13
	ds_bpermute_b32 v13, v6, v12
	s_waitcnt lgkmcnt(0)
	v_add_f32_e32 v12, v12, v13
	ds_bpermute_b32 v13, v7, v12
	s_waitcnt lgkmcnt(0)
	v_add_f32_e32 v12, v12, v13
	ds_bpermute_b32 v13, v8, v12
	s_waitcnt lgkmcnt(0)
	v_add_f32_e32 v12, v12, v13
	ds_bpermute_b32 v13, v9, v12
	s_waitcnt lgkmcnt(0)
	v_add_f32_e32 v12, v12, v13
	v_fmamk_f32 v12, v12, 0x3a800000, v16
	v_cmp_gt_f32_e32 vcc, 0x800000, v12
	v_mul_f32_e32 v13, 0x4b800000, v12
	s_nop 0
	v_cndmask_b32_e32 v12, v12, v13, vcc
	v_rsq_f32_e32 v12, v12
	s_nop 0
	v_mul_f32_e32 v13, 0x45800000, v12
	v_cndmask_b32_e32 v14, v12, v13, vcc
	s_lshl_b32 s12, s7, 11
	s_lshr_b32 s13, s7, 21
	s_add_u32 s12, s64, s12
	s_addc_u32 s13, s65, s13
	v_pk_mul_f32 v[40:41], v[40:41], v[14:15] op_sel_hi:[1,0]
	v_pk_mul_f32 v[40:41], v[136:137], v[40:41]
	v_pk_add_f32 v[56:57], v[56:57], 1.0 op_sel_hi:[1,0]
	v_pk_fma_f32 v[40:41], v[56:57], v[40:41], v[72:73]
	v_pk_mul_f32 v[42:43], v[42:43], v[14:15] op_sel_hi:[1,0]
	v_pk_mul_f32 v[42:43], v[138:139], v[42:43]
	v_pk_add_f32 v[58:59], v[58:59], 1.0 op_sel_hi:[1,0]
	v_pk_fma_f32 v[42:43], v[58:59], v[42:43], v[74:75]
	v_cvt_pk_f16_f32 v40, v40, v41
	v_cvt_pk_f16_f32 v41, v42, v43
	global_store_dwordx2 v3, v[40:41], s[12:13] offset:0
	v_pk_mul_f32 v[44:45], v[44:45], v[14:15] op_sel_hi:[1,0]
	v_pk_mul_f32 v[44:45], v[140:141], v[44:45]
	v_pk_add_f32 v[60:61], v[60:61], 1.0 op_sel_hi:[1,0]
	v_pk_fma_f32 v[44:45], v[60:61], v[44:45], v[76:77]
	v_pk_mul_f32 v[46:47], v[46:47], v[14:15] op_sel_hi:[1,0]
	v_pk_mul_f32 v[46:47], v[142:143], v[46:47]
	v_pk_add_f32 v[62:63], v[62:63], 1.0 op_sel_hi:[1,0]
	v_pk_fma_f32 v[46:47], v[62:63], v[46:47], v[78:79]
	v_cvt_pk_f16_f32 v44, v44, v45
	v_cvt_pk_f16_f32 v45, v46, v47
	global_store_dwordx2 v3, v[44:45], s[12:13] offset:512
	v_pk_mul_f32 v[48:49], v[48:49], v[14:15] op_sel_hi:[1,0]
	v_pk_mul_f32 v[48:49], v[144:145], v[48:49]
	v_pk_add_f32 v[64:65], v[64:65], 1.0 op_sel_hi:[1,0]
	v_pk_fma_f32 v[48:49], v[64:65], v[48:49], v[80:81]
	v_pk_mul_f32 v[50:51], v[50:51], v[14:15] op_sel_hi:[1,0]
	v_pk_mul_f32 v[50:51], v[146:147], v[50:51]
	v_pk_add_f32 v[66:67], v[66:67], 1.0 op_sel_hi:[1,0]
	v_pk_fma_f32 v[50:51], v[66:67], v[50:51], v[82:83]
	v_cvt_pk_f16_f32 v48, v48, v49
	v_cvt_pk_f16_f32 v49, v50, v51
	global_store_dwordx2 v3, v[48:49], s[12:13] offset:1024
	v_pk_mul_f32 v[52:53], v[52:53], v[14:15] op_sel_hi:[1,0]
	v_pk_mul_f32 v[52:53], v[148:149], v[52:53]
	v_pk_add_f32 v[68:69], v[68:69], 1.0 op_sel_hi:[1,0]
	v_pk_fma_f32 v[52:53], v[68:69], v[52:53], v[84:85]
	v_pk_mul_f32 v[54:55], v[54:55], v[14:15] op_sel_hi:[1,0]
	v_pk_mul_f32 v[54:55], v[150:151], v[54:55]
	v_pk_add_f32 v[70:71], v[70:71], 1.0 op_sel_hi:[1,0]
	v_pk_fma_f32 v[54:55], v[70:71], v[54:55], v[86:87]
	v_cvt_pk_f16_f32 v52, v52, v53
	v_cvt_pk_f16_f32 v53, v54, v55
	global_store_dwordx2 v3, v[52:53], s[12:13] offset:1536
	s_waitcnt vmcnt(4)
	s_mov_b32 s7, s4
	s_add_i32 s4, s7, s3
	s_cmp_lt_i32 s4, 0x9000
	s_cbranch_scc0 .Ln1p_last1
	s_cmp_lt_u32 s4, 0x8000
	s_cselect_b32 s10, s22, s24
	s_cselect_b32 s11, s23, s25
	s_cselect_b32 s5, s4, 0x8000
	s_and_b32 s26, s4, 0x7fff
	s_lshl_b32 s27, s26, 12
	s_lshr_b32 s26, s26, 20
	s_add_u32 s10, s10, s27
	s_addc_u32 s11, s11, s26
	s_lshr_b32 s5, s5, 11
	s_mul_i32 s5, s5, 0x6000
	s_add_u32 s14, s20, s5
	s_addc_u32 s15, s21, 0
	s_add_u32 s16, s14, 0x0
	s_addc_u32 s17, s15, 0
	s_add_u32 s14, s14, 0x1000
	s_addc_u32 s15, s15, 0
	global_load_dwordx4 v[40:43], v2, s[10:11] offset:0
	global_load_dwordx4 v[44:47], v2, s[10:11] offset:1024
	global_load_dwordx4 v[48:51], v2, s[10:11] offset:2048
	global_load_dwordx4 v[52:55], v2, s[10:11] offset:3072
	global_load_dwordx4 v[56:59], v2, s[14:15] offset:0
	global_load_dwordx4 v[60:63], v2, s[14:15] offset:1024
	global_load_dwordx4 v[64:67], v2, s[14:15] offset:2048
	global_load_dwordx4 v[68:71], v2, s[14:15] offset:3072
	global_load_dwordx4 v[72:75], v2, s[16:17] offset:0
	global_load_dwordx4 v[76:79], v2, s[16:17] offset:1024
	global_load_dwordx4 v[80:83], v2, s[16:17] offset:2048
	global_load_dwordx4 v[84:87], v2, s[16:17] offset:3072
	v_mul_f32_e32 v12, v88, v88
	v_fmac_f32_e32 v12, v89, v89
	v_fmac_f32_e32 v12, v90, v90
	v_fmac_f32_e32 v12, v91, v91
	v_fmac_f32_e32 v12, v92, v92
	v_fmac_f32_e32 v12, v93, v93
	v_fmac_f32_e32 v12, v94, v94
	v_fmac_f32_e32 v12, v95, v95
	v_fmac_f32_e32 v12, v96, v96
	v_fmac_f32_e32 v12, v97, v97
	v_fmac_f32_e32 v12, v98, v98
	v_fmac_f32_e32 v12, v99, v99
	v_fmac_f32_e32 v12, v100, v100
	v_fmac_f32_e32 v12, v101, v101
	v_fmac_f32_e32 v12, v102, v102
	v_fmac_f32_e32 v12, v103, v103
	ds_bpermute_b32 v13, v4, v12
	s_waitcnt lgkmcnt(0)
	v_add_f32_e32 v12, v12, v13
	ds_bpermute_b32 v13, v5, v12
	s_waitcnt lgkmcnt(0)
	v_add_f32_e32 v12, v12, v13
	ds_bpermute_b32 v13, v6, v12
	s_waitcnt lgkmcnt(0)
	v_add_f32_e32 v12, v12, v13
	ds_bpermute_b32 v13, v7, v12
	s_waitcnt lgkmcnt(0)
	v_add_f32_e32 v12, v12, v13
	ds_bpermute_b32 v13, v8, v12
	s_waitcnt lgkmcnt(0)
	v_add_f32_e32 v12, v12, v13
	ds_bpermute_b32 v13, v9, v12
	s_waitcnt lgkmcnt(0)
	v_add_f32_e32 v12, v12, v13
	v_fmamk_f32 v12, v12, 0x3a800000, v16
	v_cmp_gt_f32_e32 vcc, 0x800000, v12
	v_mul_f32_e32 v13, 0x4b800000, v12
	s_nop 0
	v_cndmask_b32_e32 v12, v12, v13, vcc
	v_rsq_f32_e32 v12, v12
	s_nop 0
	v_mul_f32_e32 v13, 0x45800000, v12
	v_cndmask_b32_e32 v14, v12, v13, vcc
	s_lshl_b32 s12, s7, 11
	s_lshr_b32 s13, s7, 21
	s_add_u32 s12, s64, s12
	s_addc_u32 s13, s65, s13
	v_pk_mul_f32 v[88:89], v[88:89], v[14:15] op_sel_hi:[1,0]
	v_pk_mul_f32 v[88:89], v[136:137], v[88:89]
	v_pk_add_f32 v[104:105], v[104:105], 1.0 op_sel_hi:[1,0]
	v_pk_fma_f32 v[88:89], v[104:105], v[88:89], v[120:121]
	v_pk_mul_f32 v[90:91], v[90:91], v[14:15] op_sel_hi:[1,0]
	v_pk_mul_f32 v[90:91], v[138:139], v[90:91]
	v_pk_add_f32 v[106:107], v[106:107], 1.0 op_sel_hi:[1,0]
	v_pk_fma_f32 v[90:91], v[106:107], v[90:91], v[122:123]
	v_cvt_pk_f16_f32 v88, v88, v89
	v_cvt_pk_f16_f32 v89, v90, v91
	global_store_dwordx2 v3, v[88:89], s[12:13] offset:0
	v_pk_mul_f32 v[92:93], v[92:93], v[14:15] op_sel_hi:[1,0]
	v_pk_mul_f32 v[92:93], v[140:141], v[92:93]
	v_pk_add_f32 v[108:109], v[108:109], 1.0 op_sel_hi:[1,0]
	v_pk_fma_f32 v[92:93], v[108:109], v[92:93], v[124:125]
	v_pk_mul_f32 v[94:95], v[94:95], v[14:15] op_sel_hi:[1,0]
	v_pk_mul_f32 v[94:95], v[142:143], v[94:95]
	v_pk_add_f32 v[110:111], v[110:111], 1.0 op_sel_hi:[1,0]
	v_pk_fma_f32 v[94:95], v[110:111], v[94:95], v[126:127]
	v_cvt_pk_f16_f32 v92, v92, v93
	v_cvt_pk_f16_f32 v93, v94, v95
	global_store_dwordx2 v3, v[92:93], s[12:13] offset:512
	v_pk_mul_f32 v[96:97], v[96:97], v[14:15] op_sel_hi:[1,0]
	v_pk_mul_f32 v[96:97], v[144:145], v[96:97]
	v_pk_add_f32 v[112:113], v[112:113], 1.0 op_sel_hi:[1,0]
	v_pk_fma_f32 v[96:97], v[112:113], v[96:97], v[128:129]
	v_pk_mul_f32 v[98:99], v[98:99], v[14:15] op_sel_hi:[1,0]
	v_pk_mul_f32 v[98:99], v[146:147], v[98:99]
	v_pk_add_f32 v[114:115], v[114:115], 1.0 op_sel_hi:[1,0]
	v_pk_fma_f32 v[98:99], v[114:115], v[98:99], v[130:131]
	v_cvt_pk_f16_f32 v96, v96, v97
	v_cvt_pk_f16_f32 v97, v98, v99
	global_store_dwordx2 v3, v[96:97], s[12:13] offset:1024
	v_pk_mul_f32 v[100:101], v[100:101], v[14:15] op_sel_hi:[1,0]
	v_pk_mul_f32 v[100:101], v[148:149], v[100:101]
	v_pk_add_f32 v[116:117], v[116:117], 1.0 op_sel_hi:[1,0]
	v_pk_fma_f32 v[100:101], v[116:117], v[100:101], v[132:133]
	v_pk_mul_f32 v[102:103], v[102:103], v[14:15] op_sel_hi:[1,0]
	v_pk_mul_f32 v[102:103], v[150:151], v[102:103]
	v_pk_add_f32 v[118:119], v[118:119], 1.0 op_sel_hi:[1,0]
	v_pk_fma_f32 v[102:103], v[118:119], v[102:103], v[134:135]
	v_cvt_pk_f16_f32 v100, v100, v101
	v_cvt_pk_f16_f32 v101, v102, v103
	global_store_dwordx2 v3, v[100:101], s[12:13] offset:1536
	s_waitcnt vmcnt(4)
	s_mov_b32 s7, s4
	s_branch .Ln1p_loop
.Ln1p_last0:
	v_mul_f32_e32 v12, v40, v40
	v_fmac_f32_e32 v12, v41, v41
	v_fmac_f32_e32 v12, v42, v42
	v_fmac_f32_e32 v12, v43, v43
	v_fmac_f32_e32 v12, v44, v44
	v_fmac_f32_e32 v12, v45, v45
	v_fmac_f32_e32 v12, v46, v46
	v_fmac_f32_e32 v12, v47, v47
	v_fmac_f32_e32 v12, v48, v48
	v_fmac_f32_e32 v12, v49, v49
	v_fmac_f32_e32 v12, v50, v50
	v_fmac_f32_e32 v12, v51, v51
	v_fmac_f32_e32 v12, v52, v52
	v_fmac_f32_e32 v12, v53, v53
	v_fmac_f32_e32 v12, v54, v54
	v_fmac_f32_e32 v12, v55, v55
	ds_bpermute_b32 v13, v4, v12
	s_waitcnt lgkmcnt(0)
	v_add_f32_e32 v12, v12, v13
	ds_bpermute_b32 v13, v5, v12
	s_waitcnt lgkmcnt(0)
	v_add_f32_e32 v12, v12, v13
	ds_bpermute_b32 v13, v6, v12
	s_waitcnt lgkmcnt(0)
	v_add_f32_e32 v12, v12, v13
	ds_bpermute_b32 v13, v7, v12
	s_waitcnt lgkmcnt(0)
	v_add_f32_e32 v12, v12, v13
	ds_bpermute_b32 v13, v8, v12
	s_waitcnt lgkmcnt(0)
	v_add_f32_e32 v12, v12, v13
	ds_bpermute_b32 v13, v9, v12
	s_waitcnt lgkmcnt(0)
	v_add_f32_e32 v12, v12, v13
	v_fmamk_f32 v12, v12, 0x3a800000, v16
	v_cmp_gt_f32_e32 vcc, 0x800000, v12
	v_mul_f32_e32 v13, 0x4b800000, v12
	s_nop 0
	v_cndmask_b32_e32 v12, v12, v13, vcc
	v_rsq_f32_e32 v12, v12
	s_nop 0
	v_mul_f32_e32 v13, 0x45800000, v12
	v_cndmask_b32_e32 v14, v12, v13, vcc
	s_lshl_b32 s12, s7, 11
	s_lshr_b32 s13, s7, 21
	s_add_u32 s12, s64, s12
	s_addc_u32 s13, s65, s13
	v_pk_mul_f32 v[40:41], v[40:41], v[14:15] op_sel_hi:[1,0]
	v_pk_mul_f32 v[40:41], v[136:137], v[40:41]
	v_pk_add_f32 v[56:57], v[56:57], 1.0 op_sel_hi:[1,0]
	v_pk_fma_f32 v[40:41], v[56:57], v[40:41], v[72:73]
	v_pk_mul_f32 v[42:43], v[42:43], v[14:15] op_sel_hi:[1,0]
	v_pk_mul_f32 v[42:43], v[138:139], v[42:43]
	v_pk_add_f32 v[58:59], v[58:59], 1.0 op_sel_hi:[1,0]
	v_pk_fma_f32 v[42:43], v[58:59], v[42:43], v[74:75]
	v_cvt_pk_f16_f32 v40, v40, v41
	v_cvt_pk_f16_f32 v41, v42, v43
	global_store_dwordx2 v3, v[40:41], s[12:13] offset:0
	v_pk_mul_f32 v[44:45], v[44:45], v[14:15] op_sel_hi:[1,0]
	v_pk_mul_f32 v[44:45], v[140:141], v[44:45]
	v_pk_add_f32 v[60:61], v[60:61], 1.0 op_sel_hi:[1,0]
	v_pk_fma_f32 v[44:45], v[60:61], v[44:45], v[76:77]
	v_pk_mul_f32 v[46:47], v[46:47], v[14:15] op_sel_hi:[1,0]
	v_pk_mul_f32 v[46:47], v[142:143], v[46:47]
	v_pk_add_f32 v[62:63], v[62:63], 1.0 op_sel_hi:[1,0]
	v_pk_fma_f32 v[46:47], v[62:63], v[46:47], v[78:79]
	v_cvt_pk_f16_f32 v44, v44, v45
	v_cvt_pk_f16_f32 v45, v46, v47
	global_store_dwordx2 v3, v[44:45], s[12:13] offset:512
	v_pk_mul_f32 v[48:49], v[48:49], v[14:15] op_sel_hi:[1,0]
	v_pk_mul_f32 v[48:49], v[144:145], v[48:49]
	v_pk_add_f32 v[64:65], v[64:65], 1.0 op_sel_hi:[1,0]
	v_pk_fma_f32 v[48:49], v[64:65], v[48:49], v[80:81]
	v_pk_mul_f32 v[50:51], v[50:51], v[14:15] op_sel_hi:[1,0]
	v_pk_mul_f32 v[50:51], v[146:147], v[50:51]
	v_pk_add_f32 v[66:67], v[66:67], 1.0 op_sel_hi:[1,0]
	v_pk_fma_f32 v[50:51], v[66:67], v[50:51], v[82:83]
	v_cvt_pk_f16_f32 v48, v48, v49
	v_cvt_pk_f16_f32 v49, v50, v51
	global_store_dwordx2 v3, v[48:49], s[12:13] offset:1024
	v_pk_mul_f32 v[52:53], v[52:53], v[14:15] op_sel_hi:[1,0]
	v_pk_mul_f32 v[52:53], v[148:149], v[52:53]
	v_pk_add_f32 v[68:69], v[68:69], 1.0 op_sel_hi:[1,0]
	v_pk_fma_f32 v[52:53], v[68:69], v[52:53], v[84:85]
	v_pk_mul_f32 v[54:55], v[54:55], v[14:15] op_sel_hi:[1,0]
	v_pk_mul_f32 v[54:55], v[150:151], v[54:55]
	v_pk_add_f32 v[70:71], v[70:71], 1.0 op_sel_hi:[1,0]
	v_pk_fma_f32 v[54:55], v[70:71], v[54:55], v[86:87]
	v_cvt_pk_f16_f32 v52, v52, v53
	v_cvt_pk_f16_f32 v53, v54, v55
	global_store_dwordx2 v3, v[52:53], s[12:13] offset:1536
	s_branch .Ln1p_done
.Ln1p_last1:
	v_mul_f32_e32 v12, v88, v88
	v_fmac_f32_e32 v12, v89, v89
	v_fmac_f32_e32 v12, v90, v90
	v_fmac_f32_e32 v12, v91, v91
	v_fmac_f32_e32 v12, v92, v92
	v_fmac_f32_e32 v12, v93, v93
	v_fmac_f32_e32 v12, v94, v94
	v_fmac_f32_e32 v12, v95, v95
	v_fmac_f32_e32 v12, v96, v96
	v_fmac_f32_e32 v12, v97, v97
	v_fmac_f32_e32 v12, v98, v98
	v_fmac_f32_e32 v12, v99, v99
	v_fmac_f32_e32 v12, v100, v100
	v_fmac_f32_e32 v12, v101, v101
	v_fmac_f32_e32 v12, v102, v102
	v_fmac_f32_e32 v12, v103, v103
	ds_bpermute_b32 v13, v4, v12
	s_waitcnt lgkmcnt(0)
	v_add_f32_e32 v12, v12, v13
	ds_bpermute_b32 v13, v5, v12
	s_waitcnt lgkmcnt(0)
	v_add_f32_e32 v12, v12, v13
	ds_bpermute_b32 v13, v6, v12
	s_waitcnt lgkmcnt(0)
	v_add_f32_e32 v12, v12, v13
	ds_bpermute_b32 v13, v7, v12
	s_waitcnt lgkmcnt(0)
	v_add_f32_e32 v12, v12, v13
	ds_bpermute_b32 v13, v8, v12
	s_waitcnt lgkmcnt(0)
	v_add_f32_e32 v12, v12, v13
	ds_bpermute_b32 v13, v9, v12
	s_waitcnt lgkmcnt(0)
	v_add_f32_e32 v12, v12, v13
	v_fmamk_f32 v12, v12, 0x3a800000, v16
	v_cmp_gt_f32_e32 vcc, 0x800000, v12
	v_mul_f32_e32 v13, 0x4b800000, v12
	s_nop 0
	v_cndmask_b32_e32 v12, v12, v13, vcc
	v_rsq_f32_e32 v12, v12
	s_nop 0
	v_mul_f32_e32 v13, 0x45800000, v12
	v_cndmask_b32_e32 v14, v12, v13, vcc
	s_lshl_b32 s12, s7, 11
	s_lshr_b32 s13, s7, 21
	s_add_u32 s12, s64, s12
	s_addc_u32 s13, s65, s13
	v_pk_mul_f32 v[88:89], v[88:89], v[14:15] op_sel_hi:[1,0]
	v_pk_mul_f32 v[88:89], v[136:137], v[88:89]
	v_pk_add_f32 v[104:105], v[104:105], 1.0 op_sel_hi:[1,0]
	v_pk_fma_f32 v[88:89], v[104:105], v[88:89], v[120:121]
	v_pk_mul_f32 v[90:91], v[90:91], v[14:15] op_sel_hi:[1,0]
	v_pk_mul_f32 v[90:91], v[138:139], v[90:91]
	v_pk_add_f32 v[106:107], v[106:107], 1.0 op_sel_hi:[1,0]
	v_pk_fma_f32 v[90:91], v[106:107], v[90:91], v[122:123]
	v_cvt_pk_f16_f32 v88, v88, v89
	v_cvt_pk_f16_f32 v89, v90, v91
	global_store_dwordx2 v3, v[88:89], s[12:13] offset:0
	v_pk_mul_f32 v[92:93], v[92:93], v[14:15] op_sel_hi:[1,0]
	v_pk_mul_f32 v[92:93], v[140:141], v[92:93]
	v_pk_add_f32 v[108:109], v[108:109], 1.0 op_sel_hi:[1,0]
	v_pk_fma_f32 v[92:93], v[108:109], v[92:93], v[124:125]
	v_pk_mul_f32 v[94:95], v[94:95], v[14:15] op_sel_hi:[1,0]
	v_pk_mul_f32 v[94:95], v[142:143], v[94:95]
	v_pk_add_f32 v[110:111], v[110:111], 1.0 op_sel_hi:[1,0]
	v_pk_fma_f32 v[94:95], v[110:111], v[94:95], v[126:127]
	v_cvt_pk_f16_f32 v92, v92, v93
	v_cvt_pk_f16_f32 v93, v94, v95
	global_store_dwordx2 v3, v[92:93], s[12:13] offset:512
	v_pk_mul_f32 v[96:97], v[96:97], v[14:15] op_sel_hi:[1,0]
	v_pk_mul_f32 v[96:97], v[144:145], v[96:97]
	v_pk_add_f32 v[112:113], v[112:113], 1.0 op_sel_hi:[1,0]
	v_pk_fma_f32 v[96:97], v[112:113], v[96:97], v[128:129]
	v_pk_mul_f32 v[98:99], v[98:99], v[14:15] op_sel_hi:[1,0]
	v_pk_mul_f32 v[98:99], v[146:147], v[98:99]
	v_pk_add_f32 v[114:115], v[114:115], 1.0 op_sel_hi:[1,0]
	v_pk_fma_f32 v[98:99], v[114:115], v[98:99], v[130:131]
	v_cvt_pk_f16_f32 v96, v96, v97
	v_cvt_pk_f16_f32 v97, v98, v99
	global_store_dwordx2 v3, v[96:97], s[12:13] offset:1024
	v_pk_mul_f32 v[100:101], v[100:101], v[14:15] op_sel_hi:[1,0]
	v_pk_mul_f32 v[100:101], v[148:149], v[100:101]
	v_pk_add_f32 v[116:117], v[116:117], 1.0 op_sel_hi:[1,0]
	v_pk_fma_f32 v[100:101], v[116:117], v[100:101], v[132:133]
	v_pk_mul_f32 v[102:103], v[102:103], v[14:15] op_sel_hi:[1,0]
	v_pk_mul_f32 v[102:103], v[150:151], v[102:103]
	v_pk_add_f32 v[118:119], v[118:119], 1.0 op_sel_hi:[1,0]
	v_pk_fma_f32 v[102:103], v[118:119], v[102:103], v[134:135]
	v_cvt_pk_f16_f32 v100, v100, v101
	v_cvt_pk_f16_f32 v101, v102, v103
	global_store_dwordx2 v3, v[100:101], s[12:13] offset:1536
.Ln1p_done:
	v_readlane_b32 s16, v254, 0
	v_readlane_b32 s17, v254, 1
	v_readlane_b32 s18, v254, 2
	v_readlane_b32 s19, v254, 3
	v_readlane_b32 s20, v254, 4
	v_readlane_b32 s21, v254, 5
	v_readlane_b32 s22, v254, 6
	v_readlane_b32 s23, v254, 7
	v_readlane_b32 s24, v254, 8
	v_readlane_b32 s25, v254, 9
	v_readlane_b32 s26, v254, 10
	v_readlane_b32 s27, v254, 11
	v_readlane_b32 s28, v254, 12
	v_readlane_b32 s29, v254, 13
	v_readlane_b32 s30, v254, 14
	v_readlane_b32 s31, v254, 15
	s_branch .LBB0_304

.LBB0_1071:
	s_or_b64 exec, exec, s[2:3]
	v_mov_b32_e32 v1, v222
	s_barrier
	v_readlane_b32 s2, v254, 57
	v_ashrrev_i32_e32 v2, 6, v1
	s_nop 0
	v_add_u32_e32 v18, s2, v2
	v_cmp_gt_i32_e32 vcc, s6, v18
	s_and_saveexec_b64 s[2:3], vcc
	s_cbranch_execz .LBB0_1078
	v_readfirstlane_b32 s7, v18
	v_mbcnt_lo_u32_b32 v10, -1, 0
	v_mbcnt_hi_u32_b32 v10, -1, v10
	v_lshlrev_b32_e32 v2, 4, v10
	v_lshlrev_b32_e32 v3, 3, v10
	v_xor_b32_e32 v4, 32, v10
	v_lshlrev_b32_e32 v4, 2, v4
	v_xor_b32_e32 v5, 16, v10
	v_lshlrev_b32_e32 v5, 2, v5
	v_xor_b32_e32 v6, 8, v10
	v_lshlrev_b32_e32 v6, 2, v6
	v_xor_b32_e32 v7, 4, v10
	v_lshlrev_b32_e32 v7, 2, v7
	v_xor_b32_e32 v8, 2, v10
	v_lshlrev_b32_e32 v8, 2, v8
	v_xor_b32_e32 v9, 1, v10
	v_lshlrev_b32_e32 v9, 2, v9
	v_mov_b32_e32 v16, 0x358637bd
	v_readlane_b32 s22, v254, 12
	v_readlane_b32 s23, v254, 13
	v_readlane_b32 s24, v254, 55
	v_readlane_b32 s25, v254, 56
	v_readlane_b32 s20, v254, 14
	v_readlane_b32 s21, v254, 15
	v_readlane_b32 s18, v254, 60
	v_readlane_b32 s19, v254, 61
	v_readlane_b32 s5, v255, 47
	s_lshl_b32 s5, s5, 12
	s_add_u32 s18, s18, s5
	s_addc_u32 s19, s19, 0
	s_nop 4
	global_load_dwordx4 v[136:139], v2, s[18:19] offset:0
	global_load_dwordx4 v[140:143], v2, s[18:19] offset:1024
	global_load_dwordx4 v[144:147], v2, s[18:19] offset:2048
	global_load_dwordx4 v[148:151], v2, s[18:19] offset:3072
	s_cmp_lt_u32 s7, 0x8000
	s_cselect_b32 s10, s22, s24
	s_cselect_b32 s11, s23, s25
	s_cselect_b32 s5, s7, 0x8000
	s_and_b32 s26, s7, 0x7fff
	s_lshl_b32 s27, s26, 12
	s_lshr_b32 s26, s26, 20
	s_add_u32 s10, s10, s27
	s_addc_u32 s11, s11, s26
	s_lshr_b32 s5, s5, 11
	s_add_i32 s5, s5, s54
	s_mul_i32 s5, s5, 0x6000
	s_add_u32 s14, s20, s5
	s_addc_u32 s15, s21, 0
	s_add_u32 s16, s14, 0x3000
	s_addc_u32 s17, s15, 0
	s_add_u32 s14, s14, 0x4000
	s_addc_u32 s15, s15, 0
	global_load_dwordx4 v[40:43], v2, s[10:11] offset:0
	global_load_dwordx4 v[44:47], v2, s[10:11] offset:1024
	global_load_dwordx4 v[48:51], v2, s[10:11] offset:2048
	global_load_dwordx4 v[52:55], v2, s[10:11] offset:3072
	global_load_dwordx4 v[56:59], v2, s[14:15] offset:0
	global_load_dwordx4 v[60:63], v2, s[14:15] offset:1024
	global_load_dwordx4 v[64:67], v2, s[14:15] offset:2048
	global_load_dwordx4 v[68:71], v2, s[14:15] offset:3072
	global_load_dwordx4 v[72:75], v2, s[16:17] offset:0
	global_load_dwordx4 v[76:79], v2, s[16:17] offset:1024
	global_load_dwordx4 v[80:83], v2, s[16:17] offset:2048
	global_load_dwordx4 v[84:87], v2, s[16:17] offset:3072
	s_waitcnt vmcnt(0)
.Ln2_loop:
	s_add_i32 s4, s7, s37
	s_cmp_lt_i32 s4, s6
	s_cbranch_scc0 .Ln2_last0
	s_cmp_lt_u32 s4, 0x8000
	s_cselect_b32 s10, s22, s24
	s_cselect_b32 s11, s23, s25
	s_cselect_b32 s5, s4, 0x8000
	s_and_b32 s26, s4, 0x7fff
	s_lshl_b32 s27, s26, 12
	s_lshr_b32 s26, s26, 20
	s_add_u32 s10, s10, s27
	s_addc_u32 s11, s11, s26
	s_lshr_b32 s5, s5, 11
	s_add_i32 s5, s5, s54
	s_mul_i32 s5, s5, 0x6000
	s_add_u32 s14, s20, s5
	s_addc_u32 s15, s21, 0
	s_add_u32 s16, s14, 0x3000
	s_addc_u32 s17, s15, 0
	s_add_u32 s14, s14, 0x4000
	s_addc_u32 s15, s15, 0
	global_load_dwordx4 v[88:91], v2, s[10:11] offset:0
	global_load_dwordx4 v[92:95], v2, s[10:11] offset:1024
	global_load_dwordx4 v[96:99], v2, s[10:11] offset:2048
	global_load_dwordx4 v[100:103], v2, s[10:11] offset:3072
	global_load_dwordx4 v[104:107], v2, s[14:15] offset:0
	global_load_dwordx4 v[108:111], v2, s[14:15] offset:1024
	global_load_dwordx4 v[112:115], v2, s[14:15] offset:2048
	global_load_dwordx4 v[116:119], v2, s[14:15] offset:3072
	global_load_dwordx4 v[120:123], v2, s[16:17] offset:0
	global_load_dwordx4 v[124:127], v2, s[16:17] offset:1024
	global_load_dwordx4 v[128:131], v2, s[16:17] offset:2048
	global_load_dwordx4 v[132:135], v2, s[16:17] offset:3072
	v_mul_f32_e32 v12, v40, v40
	v_fmac_f32_e32 v12, v41, v41
	v_fmac_f32_e32 v12, v42, v42
	v_fmac_f32_e32 v12, v43, v43
	v_fmac_f32_e32 v12, v44, v44
	v_fmac_f32_e32 v12, v45, v45
	v_fmac_f32_e32 v12, v46, v46
	v_fmac_f32_e32 v12, v47, v47
	v_fmac_f32_e32 v12, v48, v48
	v_fmac_f32_e32 v12, v49, v49
	v_fmac_f32_e32 v12, v50, v50
	v_fmac_f32_e32 v12, v51, v51
	v_fmac_f32_e32 v12, v52, v52
	v_fmac_f32_e32 v12, v53, v53
	v_fmac_f32_e32 v12, v54, v54
	v_fmac_f32_e32 v12, v55, v55
	ds_bpermute_b32 v13, v4, v12
	s_waitcnt lgkmcnt(0)
	v_add_f32_e32 v12, v12, v13
	ds_bpermute_b32 v13, v5, v12
	s_waitcnt lgkmcnt(0)
	v_add_f32_e32 v12, v12, v13
	ds_bpermute_b32 v13, v6, v12
	s_waitcnt lgkmcnt(0)
	v_add_f32_e32 v12, v12, v13
	ds_bpermute_b32 v13, v7, v12
	s_waitcnt lgkmcnt(0)
	v_add_f32_e32 v12, v12, v13
	ds_bpermute_b32 v13, v8, v12
	s_waitcnt lgkmcnt(0)
	v_add_f32_e32 v12, v12, v13
	ds_bpermute_b32 v13, v9, v12
	s_waitcnt lgkmcnt(0)
	v_add_f32_e32 v12, v12, v13
	v_fmamk_f32 v12, v12, 0x3a800000, v16
	v_cmp_gt_f32_e32 vcc, 0x800000, v12
	v_mul_f32_e32 v13, 0x4b800000, v12
	s_nop 0
	v_cndmask_b32_e32 v12, v12, v13, vcc
	v_rsq_f32_e32 v12, v12
	s_nop 0
	v_mul_f32_e32 v13, 0x45800000, v12
	v_cndmask_b32_e32 v14, v12, v13, vcc
	s_lshl_b32 s12, s7, 11
	s_lshr_b32 s13, s7, 21
	s_add_u32 s12, s64, s12
	s_addc_u32 s13, s65, s13
	v_pk_mul_f32 v[40:41], v[40:41], v[14:15] op_sel_hi:[1,0]
	v_pk_mul_f32 v[40:41], v[136:137], v[40:41]
	v_pk_add_f32 v[56:57], v[56:57], 1.0 op_sel_hi:[1,0]
	v_pk_fma_f32 v[40:41], v[56:57], v[40:41], v[72:73]
	v_pk_mul_f32 v[42:43], v[42:43], v[14:15] op_sel_hi:[1,0]
	v_pk_mul_f32 v[42:43], v[138:139], v[42:43]
	v_pk_add_f32 v[58:59], v[58:59], 1.0 op_sel_hi:[1,0]
	v_pk_fma_f32 v[42:43], v[58:59], v[42:43], v[74:75]
	v_cvt_pk_f16_f32 v40, v40, v41
	v_cvt_pk_f16_f32 v41, v42, v43
	global_store_dwordx2 v3, v[40:41], s[12:13] offset:0
	v_pk_mul_f32 v[44:45], v[44:45], v[14:15] op_sel_hi:[1,0]
	v_pk_mul_f32 v[44:45], v[140:141], v[44:45]
	v_pk_add_f32 v[60:61], v[60:61], 1.0 op_sel_hi:[1,0]
	v_pk_fma_f32 v[44:45], v[60:61], v[44:45], v[76:77]
	v_pk_mul_f32 v[46:47], v[46:47], v[14:15] op_sel_hi:[1,0]
	v_pk_mul_f32 v[46:47], v[142:143], v[46:47]
	v_pk_add_f32 v[62:63], v[62:63], 1.0 op_sel_hi:[1,0]
	v_pk_fma_f32 v[46:47], v[62:63], v[46:47], v[78:79]
	v_cvt_pk_f16_f32 v44, v44, v45
	v_cvt_pk_f16_f32 v45, v46, v47
	global_store_dwordx2 v3, v[44:45], s[12:13] offset:512
	v_pk_mul_f32 v[48:49], v[48:49], v[14:15] op_sel_hi:[1,0]
	v_pk_mul_f32 v[48:49], v[144:145], v[48:49]
	v_pk_add_f32 v[64:65], v[64:65], 1.0 op_sel_hi:[1,0]
	v_pk_fma_f32 v[48:49], v[64:65], v[48:49], v[80:81]
	v_pk_mul_f32 v[50:51], v[50:51], v[14:15] op_sel_hi:[1,0]
	v_pk_mul_f32 v[50:51], v[146:147], v[50:51]
	v_pk_add_f32 v[66:67], v[66:67], 1.0 op_sel_hi:[1,0]
	v_pk_fma_f32 v[50:51], v[66:67], v[50:51], v[82:83]
	v_cvt_pk_f16_f32 v48, v48, v49
	v_cvt_pk_f16_f32 v49, v50, v51
	global_store_dwordx2 v3, v[48:49], s[12:13] offset:1024
	v_pk_mul_f32 v[52:53], v[52:53], v[14:15] op_sel_hi:[1,0]
	v_pk_mul_f32 v[52:53], v[148:149], v[52:53]
	v_pk_add_f32 v[68:69], v[68:69], 1.0 op_sel_hi:[1,0]
	v_pk_fma_f32 v[52:53], v[68:69], v[52:53], v[84:85]
	v_pk_mul_f32 v[54:55], v[54:55], v[14:15] op_sel_hi:[1,0]
	v_pk_mul_f32 v[54:55], v[150:151], v[54:55]
	v_pk_add_f32 v[70:71], v[70:71], 1.0 op_sel_hi:[1,0]
	v_pk_fma_f32 v[54:55], v[70:71], v[54:55], v[86:87]
	v_cvt_pk_f16_f32 v52, v52, v53
	v_cvt_pk_f16_f32 v53, v54, v55
	global_store_dwordx2 v3, v[52:53], s[12:13] offset:1536
	s_waitcnt vmcnt(4)
	s_mov_b32 s7, s4
	s_add_i32 s4, s7, s37
	s_cmp_lt_i32 s4, s6
	s_cbranch_scc0 .Ln2_last1
	s_cmp_lt_u32 s4, 0x8000
	s_cselect_b32 s10, s22, s24
	s_cselect_b32 s11, s23, s25
	s_cselect_b32 s5, s4, 0x8000
	s_and_b32 s26, s4, 0x7fff
	s_lshl_b32 s27, s26, 12
	s_lshr_b32 s26, s26, 20
	s_add_u32 s10, s10, s27
	s_addc_u32 s11, s11, s26
	s_lshr_b32 s5, s5, 11
	s_add_i32 s5, s5, s54
	s_mul_i32 s5, s5, 0x6000
	s_add_u32 s14, s20, s5
	s_addc_u32 s15, s21, 0
	s_add_u32 s16, s14, 0x3000
	s_addc_u32 s17, s15, 0
	s_add_u32 s14, s14, 0x4000
	s_addc_u32 s15, s15, 0
	global_load_dwordx4 v[40:43], v2, s[10:11] offset:0
	global_load_dwordx4 v[44:47], v2, s[10:11] offset:1024
	global_load_dwordx4 v[48:51], v2, s[10:11] offset:2048
	global_load_dwordx4 v[52:55], v2, s[10:11] offset:3072
	global_load_dwordx4 v[56:59], v2, s[14:15] offset:0
	global_load_dwordx4 v[60:63], v2, s[14:15] offset:1024
	global_load_dwordx4 v[64:67], v2, s[14:15] offset:2048
	global_load_dwordx4 v[68:71], v2, s[14:15] offset:3072
	global_load_dwordx4 v[72:75], v2, s[16:17] offset:0
	global_load_dwordx4 v[76:79], v2, s[16:17] offset:1024
	global_load_dwordx4 v[80:83], v2, s[16:17] offset:2048
	global_load_dwordx4 v[84:87], v2, s[16:17] offset:3072
	v_mul_f32_e32 v12, v88, v88
	v_fmac_f32_e32 v12, v89, v89
	v_fmac_f32_e32 v12, v90, v90
	v_fmac_f32_e32 v12, v91, v91
	v_fmac_f32_e32 v12, v92, v92
	v_fmac_f32_e32 v12, v93, v93
	v_fmac_f32_e32 v12, v94, v94
	v_fmac_f32_e32 v12, v95, v95
	v_fmac_f32_e32 v12, v96, v96
	v_fmac_f32_e32 v12, v97, v97
	v_fmac_f32_e32 v12, v98, v98
	v_fmac_f32_e32 v12, v99, v99
	v_fmac_f32_e32 v12, v100, v100
	v_fmac_f32_e32 v12, v101, v101
	v_fmac_f32_e32 v12, v102, v102
	v_fmac_f32_e32 v12, v103, v103
	ds_bpermute_b32 v13, v4, v12
	s_waitcnt lgkmcnt(0)
	v_add_f32_e32 v12, v12, v13
	ds_bpermute_b32 v13, v5, v12
	s_waitcnt lgkmcnt(0)
	v_add_f32_e32 v12, v12, v13
	ds_bpermute_b32 v13, v6, v12
	s_waitcnt lgkmcnt(0)
	v_add_f32_e32 v12, v12, v13
	ds_bpermute_b32 v13, v7, v12
	s_waitcnt lgkmcnt(0)
	v_add_f32_e32 v12, v12, v13
	ds_bpermute_b32 v13, v8, v12
	s_waitcnt lgkmcnt(0)
	v_add_f32_e32 v12, v12, v13
	ds_bpermute_b32 v13, v9, v12
	s_waitcnt lgkmcnt(0)
	v_add_f32_e32 v12, v12, v13
	v_fmamk_f32 v12, v12, 0x3a800000, v16
	v_cmp_gt_f32_e32 vcc, 0x800000, v12
	v_mul_f32_e32 v13, 0x4b800000, v12
	s_nop 0
	v_cndmask_b32_e32 v12, v12, v13, vcc
	v_rsq_f32_e32 v12, v12
	s_nop 0
	v_mul_f32_e32 v13, 0x45800000, v12
	v_cndmask_b32_e32 v14, v12, v13, vcc
	s_lshl_b32 s12, s7, 11
	s_lshr_b32 s13, s7, 21
	s_add_u32 s12, s64, s12
	s_addc_u32 s13, s65, s13
	v_pk_mul_f32 v[88:89], v[88:89], v[14:15] op_sel_hi:[1,0]
	v_pk_mul_f32 v[88:89], v[136:137], v[88:89]
	v_pk_add_f32 v[104:105], v[104:105], 1.0 op_sel_hi:[1,0]
	v_pk_fma_f32 v[88:89], v[104:105], v[88:89], v[120:121]
	v_pk_mul_f32 v[90:91], v[90:91], v[14:15] op_sel_hi:[1,0]
	v_pk_mul_f32 v[90:91], v[138:139], v[90:91]
	v_pk_add_f32 v[106:107], v[106:107], 1.0 op_sel_hi:[1,0]
	v_pk_fma_f32 v[90:91], v[106:107], v[90:91], v[122:123]
	v_cvt_pk_f16_f32 v88, v88, v89
	v_cvt_pk_f16_f32 v89, v90, v91
	global_store_dwordx2 v3, v[88:89], s[12:13] offset:0
	v_pk_mul_f32 v[92:93], v[92:93], v[14:15] op_sel_hi:[1,0]
	v_pk_mul_f32 v[92:93], v[140:141], v[92:93]
	v_pk_add_f32 v[108:109], v[108:109], 1.0 op_sel_hi:[1,0]
	v_pk_fma_f32 v[92:93], v[108:109], v[92:93], v[124:125]
	v_pk_mul_f32 v[94:95], v[94:95], v[14:15] op_sel_hi:[1,0]
	v_pk_mul_f32 v[94:95], v[142:143], v[94:95]
	v_pk_add_f32 v[110:111], v[110:111], 1.0 op_sel_hi:[1,0]
	v_pk_fma_f32 v[94:95], v[110:111], v[94:95], v[126:127]
	v_cvt_pk_f16_f32 v92, v92, v93
	v_cvt_pk_f16_f32 v93, v94, v95
	global_store_dwordx2 v3, v[92:93], s[12:13] offset:512
	v_pk_mul_f32 v[96:97], v[96:97], v[14:15] op_sel_hi:[1,0]
	v_pk_mul_f32 v[96:97], v[144:145], v[96:97]
	v_pk_add_f32 v[112:113], v[112:113], 1.0 op_sel_hi:[1,0]
	v_pk_fma_f32 v[96:97], v[112:113], v[96:97], v[128:129]
	v_pk_mul_f32 v[98:99], v[98:99], v[14:15] op_sel_hi:[1,0]
	v_pk_mul_f32 v[98:99], v[146:147], v[98:99]
	v_pk_add_f32 v[114:115], v[114:115], 1.0 op_sel_hi:[1,0]
	v_pk_fma_f32 v[98:99], v[114:115], v[98:99], v[130:131]
	v_cvt_pk_f16_f32 v96, v96, v97
	v_cvt_pk_f16_f32 v97, v98, v99
	global_store_dwordx2 v3, v[96:97], s[12:13] offset:1024
	v_pk_mul_f32 v[100:101], v[100:101], v[14:15] op_sel_hi:[1,0]
	v_pk_mul_f32 v[100:101], v[148:149], v[100:101]
	v_pk_add_f32 v[116:117], v[116:117], 1.0 op_sel_hi:[1,0]
	v_pk_fma_f32 v[100:101], v[116:117], v[100:101], v[132:133]
	v_pk_mul_f32 v[102:103], v[102:103], v[14:15] op_sel_hi:[1,0]
	v_pk_mul_f32 v[102:103], v[150:151], v[102:103]
	v_pk_add_f32 v[118:119], v[118:119], 1.0 op_sel_hi:[1,0]
	v_pk_fma_f32 v[102:103], v[118:119], v[102:103], v[134:135]
	v_cvt_pk_f16_f32 v100, v100, v101
	v_cvt_pk_f16_f32 v101, v102, v103
	global_store_dwordx2 v3, v[100:101], s[12:13] offset:1536
	s_waitcnt vmcnt(4)
	s_mov_b32 s7, s4
	s_branch .Ln2_loop

.LBB0_1185:
	v_mov_b32_e32 v1, v222
	v_readlane_b32 s2, v254, 57
	v_ashrrev_i32_e32 v2, 6, v1
	s_nop 0
	v_add_u32_e32 v18, s2, v2
	s_mov_b32 s2, 0x9000
	v_cmp_gt_i32_e32 vcc, s2, v18
	s_and_saveexec_b64 s[2:3], vcc
	s_cbranch_execz .LBB0_1192
	v_readfirstlane_b32 s7, v18
	v_mbcnt_lo_u32_b32 v10, -1, 0
	v_mbcnt_hi_u32_b32 v10, -1, v10
	v_lshlrev_b32_e32 v2, 4, v10
	v_lshlrev_b32_e32 v3, 3, v10
	v_xor_b32_e32 v4, 32, v10
	v_lshlrev_b32_e32 v4, 2, v4
	v_xor_b32_e32 v5, 16, v10
	v_lshlrev_b32_e32 v5, 2, v5
	v_xor_b32_e32 v6, 8, v10
	v_lshlrev_b32_e32 v6, 2, v6
	v_xor_b32_e32 v7, 4, v10
	v_lshlrev_b32_e32 v7, 2, v7
	v_xor_b32_e32 v8, 2, v10
	v_lshlrev_b32_e32 v8, 2, v8
	v_xor_b32_e32 v9, 1, v10
	v_lshlrev_b32_e32 v9, 2, v9
	v_mov_b32_e32 v16, 0x358637bd
	v_readlane_b32 s22, v254, 12
	v_readlane_b32 s23, v254, 13
	v_readlane_b32 s24, v254, 55
	v_readlane_b32 s25, v254, 56
	v_readlane_b32 s20, v254, 14
	v_readlane_b32 s21, v254, 15
	v_readlane_b32 s18, v255, 25
	v_readlane_b32 s19, v255, 26
	s_nop 4
	global_load_dwordx4 v[136:139], v2, s[18:19] offset:0
	global_load_dwordx4 v[140:143], v2, s[18:19] offset:1024
	global_load_dwordx4 v[144:147], v2, s[18:19] offset:2048
	global_load_dwordx4 v[148:151], v2, s[18:19] offset:3072
	s_cmp_lt_u32 s7, 0x8000
	s_cselect_b32 s10, s22, s24
	s_cselect_b32 s11, s23, s25
	s_cselect_b32 s5, s7, 0x8000
	s_and_b32 s26, s7, 0x7fff
	s_lshl_b32 s27, s26, 12
	s_lshr_b32 s26, s26, 20
	s_add_u32 s10, s10, s27
	s_addc_u32 s11, s11, s26
	s_lshr_b32 s5, s5, 11
	s_add_i32 s5, s5, 17
	s_mul_i32 s5, s5, 0x6000
	s_add_u32 s14, s20, s5
	s_addc_u32 s15, s21, 0
	s_add_u32 s16, s14, 0x0
	s_addc_u32 s17, s15, 0
	s_add_u32 s14, s14, 0x1000
	s_addc_u32 s15, s15, 0
	global_load_dwordx4 v[40:43], v2, s[10:11] offset:0
	global_load_dwordx4 v[44:47], v2, s[10:11] offset:1024
	global_load_dwordx4 v[48:51], v2, s[10:11] offset:2048
	global_load_dwordx4 v[52:55], v2, s[10:11] offset:3072
	global_load_dwordx4 v[56:59], v2, s[14:15] offset:0
	global_load_dwordx4 v[60:63], v2, s[14:15] offset:1024
	global_load_dwordx4 v[64:67], v2, s[14:15] offset:2048
	global_load_dwordx4 v[68:71], v2, s[14:15] offset:3072
	global_load_dwordx4 v[72:75], v2, s[16:17] offset:0
	global_load_dwordx4 v[76:79], v2, s[16:17] offset:1024
	global_load_dwordx4 v[80:83], v2, s[16:17] offset:2048
	global_load_dwordx4 v[84:87], v2, s[16:17] offset:3072
	s_waitcnt vmcnt(0)
.Ln1n_loop:
	s_add_i32 s4, s7, s37
	s_cmp_lt_i32 s4, 0x9000
	s_cbranch_scc0 .Ln1n_last0
	s_cmp_lt_u32 s4, 0x8000
	s_cselect_b32 s10, s22, s24
	s_cselect_b32 s11, s23, s25
	s_cselect_b32 s5, s4, 0x8000
	s_and_b32 s26, s4, 0x7fff
	s_lshl_b32 s27, s26, 12
	s_lshr_b32 s26, s26, 20
	s_add_u32 s10, s10, s27
	s_addc_u32 s11, s11, s26
	s_lshr_b32 s5, s5, 11
	s_add_i32 s5, s5, 17
	s_mul_i32 s5, s5, 0x6000
	s_add_u32 s14, s20, s5
	s_addc_u32 s15, s21, 0
	s_add_u32 s16, s14, 0x0
	s_addc_u32 s17, s15, 0
	s_add_u32 s14, s14, 0x1000
	s_addc_u32 s15, s15, 0
	global_load_dwordx4 v[88:91], v2, s[10:11] offset:0
	global_load_dwordx4 v[92:95], v2, s[10:11] offset:1024
	global_load_dwordx4 v[96:99], v2, s[10:11] offset:2048
	global_load_dwordx4 v[100:103], v2, s[10:11] offset:3072
	global_load_dwordx4 v[104:107], v2, s[14:15] offset:0
	global_load_dwordx4 v[108:111], v2, s[14:15] offset:1024
	global_load_dwordx4 v[112:115], v2, s[14:15] offset:2048
	global_load_dwordx4 v[116:119], v2, s[14:15] offset:3072
	global_load_dwordx4 v[120:123], v2, s[16:17] offset:0
	global_load_dwordx4 v[124:127], v2, s[16:17] offset:1024
	global_load_dwordx4 v[128:131], v2, s[16:17] offset:2048
	global_load_dwordx4 v[132:135], v2, s[16:17] offset:3072
	v_mul_f32_e32 v12, v40, v40
	v_fmac_f32_e32 v12, v41, v41
	v_fmac_f32_e32 v12, v42, v42
	v_fmac_f32_e32 v12, v43, v43
	v_fmac_f32_e32 v12, v44, v44
	v_fmac_f32_e32 v12, v45, v45
	v_fmac_f32_e32 v12, v46, v46
	v_fmac_f32_e32 v12, v47, v47
	v_fmac_f32_e32 v12, v48, v48
	v_fmac_f32_e32 v12, v49, v49
	v_fmac_f32_e32 v12, v50, v50
	v_fmac_f32_e32 v12, v51, v51
	v_fmac_f32_e32 v12, v52, v52
	v_fmac_f32_e32 v12, v53, v53
	v_fmac_f32_e32 v12, v54, v54
	v_fmac_f32_e32 v12, v55, v55
	ds_bpermute_b32 v13, v4, v12
	s_waitcnt lgkmcnt(0)
	v_add_f32_e32 v12, v12, v13
	ds_bpermute_b32 v13, v5, v12
	s_waitcnt lgkmcnt(0)
	v_add_f32_e32 v12, v12, v13
	ds_bpermute_b32 v13, v6, v12
	s_waitcnt lgkmcnt(0)
	v_add_f32_e32 v12, v12, v13
	ds_bpermute_b32 v13, v7, v12
	s_waitcnt lgkmcnt(0)
	v_add_f32_e32 v12, v12, v13
	ds_bpermute_b32 v13, v8, v12
	s_waitcnt lgkmcnt(0)
	v_add_f32_e32 v12, v12, v13
	ds_bpermute_b32 v13, v9, v12
	s_waitcnt lgkmcnt(0)
	v_add_f32_e32 v12, v12, v13
	v_fmamk_f32 v12, v12, 0x3a800000, v16
	v_cmp_gt_f32_e32 vcc, 0x800000, v12
	v_mul_f32_e32 v13, 0x4b800000, v12
	s_nop 0
	v_cndmask_b32_e32 v12, v12, v13, vcc
	v_rsq_f32_e32 v12, v12
	s_nop 0
	v_mul_f32_e32 v13, 0x45800000, v12
	v_cndmask_b32_e32 v14, v12, v13, vcc
	s_lshl_b32 s12, s7, 11
	s_lshr_b32 s13, s7, 21
	s_add_u32 s12, s64, s12
	s_addc_u32 s13, s65, s13
	v_pk_mul_f32 v[40:41], v[40:41], v[14:15] op_sel_hi:[1,0]
	v_pk_mul_f32 v[40:41], v[136:137], v[40:41]
	v_pk_add_f32 v[56:57], v[56:57], 1.0 op_sel_hi:[1,0]
	v_pk_fma_f32 v[40:41], v[56:57], v[40:41], v[72:73]
	v_pk_mul_f32 v[42:43], v[42:43], v[14:15] op_sel_hi:[1,0]
	v_pk_mul_f32 v[42:43], v[138:139], v[42:43]
	v_pk_add_f32 v[58:59], v[58:59], 1.0 op_sel_hi:[1,0]
	v_pk_fma_f32 v[42:43], v[58:59], v[42:43], v[74:75]
	v_cvt_pk_f16_f32 v40, v40, v41
	v_cvt_pk_f16_f32 v41, v42, v43
	global_store_dwordx2 v3, v[40:41], s[12:13] offset:0
	v_pk_mul_f32 v[44:45], v[44:45], v[14:15] op_sel_hi:[1,0]
	v_pk_mul_f32 v[44:45], v[140:141], v[44:45]
	v_pk_add_f32 v[60:61], v[60:61], 1.0 op_sel_hi:[1,0]
	v_pk_fma_f32 v[44:45], v[60:61], v[44:45], v[76:77]
	v_pk_mul_f32 v[46:47], v[46:47], v[14:15] op_sel_hi:[1,0]
	v_pk_mul_f32 v[46:47], v[142:143], v[46:47]
	v_pk_add_f32 v[62:63], v[62:63], 1.0 op_sel_hi:[1,0]
	v_pk_fma_f32 v[46:47], v[62:63], v[46:47], v[78:79]
	v_cvt_pk_f16_f32 v44, v44, v45
	v_cvt_pk_f16_f32 v45, v46, v47
	global_store_dwordx2 v3, v[44:45], s[12:13] offset:512
	v_pk_mul_f32 v[48:49], v[48:49], v[14:15] op_sel_hi:[1,0]
	v_pk_mul_f32 v[48:49], v[144:145], v[48:49]
	v_pk_add_f32 v[64:65], v[64:65], 1.0 op_sel_hi:[1,0]
	v_pk_fma_f32 v[48:49], v[64:65], v[48:49], v[80:81]
	v_pk_mul_f32 v[50:51], v[50:51], v[14:15] op_sel_hi:[1,0]
	v_pk_mul_f32 v[50:51], v[146:147], v[50:51]
	v_pk_add_f32 v[66:67], v[66:67], 1.0 op_sel_hi:[1,0]
	v_pk_fma_f32 v[50:51], v[66:67], v[50:51], v[82:83]
	v_cvt_pk_f16_f32 v48, v48, v49
	v_cvt_pk_f16_f32 v49, v50, v51
	global_store_dwordx2 v3, v[48:49], s[12:13] offset:1024
	v_pk_mul_f32 v[52:53], v[52:53], v[14:15] op_sel_hi:[1,0]
	v_pk_mul_f32 v[52:53], v[148:149], v[52:53]
	v_pk_add_f32 v[68:69], v[68:69], 1.0 op_sel_hi:[1,0]
	v_pk_fma_f32 v[52:53], v[68:69], v[52:53], v[84:85]
	v_pk_mul_f32 v[54:55], v[54:55], v[14:15] op_sel_hi:[1,0]
	v_pk_mul_f32 v[54:55], v[150:151], v[54:55]
	v_pk_add_f32 v[70:71], v[70:71], 1.0 op_sel_hi:[1,0]
	v_pk_fma_f32 v[54:55], v[70:71], v[54:55], v[86:87]
	v_cvt_pk_f16_f32 v52, v52, v53
	v_cvt_pk_f16_f32 v53, v54, v55
	global_store_dwordx2 v3, v[52:53], s[12:13] offset:1536
	s_waitcnt vmcnt(4)
	s_mov_b32 s7, s4
	s_add_i32 s4, s7, s37
	s_cmp_lt_i32 s4, 0x9000
	s_cbranch_scc0 .Ln1n_last1
	s_cmp_lt_u32 s4, 0x8000
	s_cselect_b32 s10, s22, s24
	s_cselect_b32 s11, s23, s25
	s_cselect_b32 s5, s4, 0x8000
	s_and_b32 s26, s4, 0x7fff
	s_lshl_b32 s27, s26, 12
	s_lshr_b32 s26, s26, 20
	s_add_u32 s10, s10, s27
	s_addc_u32 s11, s11, s26
	s_lshr_b32 s5, s5, 11
	s_add_i32 s5, s5, 17
	s_mul_i32 s5, s5, 0x6000
	s_add_u32 s14, s20, s5
	s_addc_u32 s15, s21, 0
	s_add_u32 s16, s14, 0x0
	s_addc_u32 s17, s15, 0
	s_add_u32 s14, s14, 0x1000
	s_addc_u32 s15, s15, 0
	global_load_dwordx4 v[40:43], v2, s[10:11] offset:0
	global_load_dwordx4 v[44:47], v2, s[10:11] offset:1024
	global_load_dwordx4 v[48:51], v2, s[10:11] offset:2048
	global_load_dwordx4 v[52:55], v2, s[10:11] offset:3072
	global_load_dwordx4 v[56:59], v2, s[14:15] offset:0
	global_load_dwordx4 v[60:63], v2, s[14:15] offset:1024
	global_load_dwordx4 v[64:67], v2, s[14:15] offset:2048
	global_load_dwordx4 v[68:71], v2, s[14:15] offset:3072
	global_load_dwordx4 v[72:75], v2, s[16:17] offset:0
	global_load_dwordx4 v[76:79], v2, s[16:17] offset:1024
	global_load_dwordx4 v[80:83], v2, s[16:17] offset:2048
	global_load_dwordx4 v[84:87], v2, s[16:17] offset:3072
	v_mul_f32_e32 v12, v88, v88
	v_fmac_f32_e32 v12, v89, v89
	v_fmac_f32_e32 v12, v90, v90
	v_fmac_f32_e32 v12, v91, v91
	v_fmac_f32_e32 v12, v92, v92
	v_fmac_f32_e32 v12, v93, v93
	v_fmac_f32_e32 v12, v94, v94
	v_fmac_f32_e32 v12, v95, v95
	v_fmac_f32_e32 v12, v96, v96
	v_fmac_f32_e32 v12, v97, v97
	v_fmac_f32_e32 v12, v98, v98
	v_fmac_f32_e32 v12, v99, v99
	v_fmac_f32_e32 v12, v100, v100
	v_fmac_f32_e32 v12, v101, v101
	v_fmac_f32_e32 v12, v102, v102
	v_fmac_f32_e32 v12, v103, v103
	ds_bpermute_b32 v13, v4, v12
	s_waitcnt lgkmcnt(0)
	v_add_f32_e32 v12, v12, v13
	ds_bpermute_b32 v13, v5, v12
	s_waitcnt lgkmcnt(0)
	v_add_f32_e32 v12, v12, v13
	ds_bpermute_b32 v13, v6, v12
	s_waitcnt lgkmcnt(0)
	v_add_f32_e32 v12, v12, v13
	ds_bpermute_b32 v13, v7, v12
	s_waitcnt lgkmcnt(0)
	v_add_f32_e32 v12, v12, v13
	ds_bpermute_b32 v13, v8, v12
	s_waitcnt lgkmcnt(0)
	v_add_f32_e32 v12, v12, v13
	ds_bpermute_b32 v13, v9, v12
	s_waitcnt lgkmcnt(0)
	v_add_f32_e32 v12, v12, v13
	v_fmamk_f32 v12, v12, 0x3a800000, v16
	v_cmp_gt_f32_e32 vcc, 0x800000, v12
	v_mul_f32_e32 v13, 0x4b800000, v12
	s_nop 0
	v_cndmask_b32_e32 v12, v12, v13, vcc
	v_rsq_f32_e32 v12, v12
	s_nop 0
	v_mul_f32_e32 v13, 0x45800000, v12
	v_cndmask_b32_e32 v14, v12, v13, vcc
	s_lshl_b32 s12, s7, 11
	s_lshr_b32 s13, s7, 21
	s_add_u32 s12, s64, s12
	s_addc_u32 s13, s65, s13
	v_pk_mul_f32 v[88:89], v[88:89], v[14:15] op_sel_hi:[1,0]
	v_pk_mul_f32 v[88:89], v[136:137], v[88:89]
	v_pk_add_f32 v[104:105], v[104:105], 1.0 op_sel_hi:[1,0]
	v_pk_fma_f32 v[88:89], v[104:105], v[88:89], v[120:121]
	v_pk_mul_f32 v[90:91], v[90:91], v[14:15] op_sel_hi:[1,0]
	v_pk_mul_f32 v[90:91], v[138:139], v[90:91]
	v_pk_add_f32 v[106:107], v[106:107], 1.0 op_sel_hi:[1,0]
	v_pk_fma_f32 v[90:91], v[106:107], v[90:91], v[122:123]
	v_cvt_pk_f16_f32 v88, v88, v89
	v_cvt_pk_f16_f32 v89, v90, v91
	global_store_dwordx2 v3, v[88:89], s[12:13] offset:0
	v_pk_mul_f32 v[92:93], v[92:93], v[14:15] op_sel_hi:[1,0]
	v_pk_mul_f32 v[92:93], v[140:141], v[92:93]
	v_pk_add_f32 v[108:109], v[108:109], 1.0 op_sel_hi:[1,0]
	v_pk_fma_f32 v[92:93], v[108:109], v[92:93], v[124:125]
	v_pk_mul_f32 v[94:95], v[94:95], v[14:15] op_sel_hi:[1,0]
	v_pk_mul_f32 v[94:95], v[142:143], v[94:95]
	v_pk_add_f32 v[110:111], v[110:111], 1.0 op_sel_hi:[1,0]
	v_pk_fma_f32 v[94:95], v[110:111], v[94:95], v[126:127]
	v_cvt_pk_f16_f32 v92, v92, v93
	v_cvt_pk_f16_f32 v93, v94, v95
	global_store_dwordx2 v3, v[92:93], s[12:13] offset:512
	v_pk_mul_f32 v[96:97], v[96:97], v[14:15] op_sel_hi:[1,0]
	v_pk_mul_f32 v[96:97], v[144:145], v[96:97]
	v_pk_add_f32 v[112:113], v[112:113], 1.0 op_sel_hi:[1,0]
	v_pk_fma_f32 v[96:97], v[112:113], v[96:97], v[128:129]
	v_pk_mul_f32 v[98:99], v[98:99], v[14:15] op_sel_hi:[1,0]
	v_pk_mul_f32 v[98:99], v[146:147], v[98:99]
	v_pk_add_f32 v[114:115], v[114:115], 1.0 op_sel_hi:[1,0]
	v_pk_fma_f32 v[98:99], v[114:115], v[98:99], v[130:131]
	v_cvt_pk_f16_f32 v96, v96, v97
	v_cvt_pk_f16_f32 v97, v98, v99
	global_store_dwordx2 v3, v[96:97], s[12:13] offset:1024
	v_pk_mul_f32 v[100:101], v[100:101], v[14:15] op_sel_hi:[1,0]
	v_pk_mul_f32 v[100:101], v[148:149], v[100:101]
	v_pk_add_f32 v[116:117], v[116:117], 1.0 op_sel_hi:[1,0]
	v_pk_fma_f32 v[100:101], v[116:117], v[100:101], v[132:133]
	v_pk_mul_f32 v[102:103], v[102:103], v[14:15] op_sel_hi:[1,0]
	v_pk_mul_f32 v[102:103], v[150:151], v[102:103]
	v_pk_add_f32 v[118:119], v[118:119], 1.0 op_sel_hi:[1,0]
	v_pk_fma_f32 v[102:103], v[118:119], v[102:103], v[134:135]
	v_cvt_pk_f16_f32 v100, v100, v101
	v_cvt_pk_f16_f32 v101, v102, v103
	global_store_dwordx2 v3, v[100:101], s[12:13] offset:1536
	s_waitcnt vmcnt(4)
	s_mov_b32 s7, s4
	s_branch .Ln1n_loop

.Ln1n_done:
	v_readlane_b32 s12, v254, 0
	v_readlane_b32 s13, v254, 1
	v_readlane_b32 s14, v254, 2
	v_readlane_b32 s15, v254, 3
	v_readlane_b32 s16, v254, 4
	v_readlane_b32 s17, v254, 5
	v_readlane_b32 s18, v254, 6
	v_readlane_b32 s19, v254, 7
	v_readlane_b32 s20, v254, 8
	v_readlane_b32 s21, v254, 9
	v_readlane_b32 s22, v254, 10
	v_readlane_b32 s23, v254, 11
	v_readlane_b32 s24, v254, 12
	v_readlane_b32 s25, v254, 13
	v_readlane_b32 s26, v254, 14
	v_readlane_b32 s27, v254, 15
	v_readlane_b32 s10, v254, 55
	v_readlane_b32 s11, v254, 56
	s_branch .LBB0_1192

.LBB0_1197:
	v_readlane_b32 s0, v254, 57
	v_ashrrev_i32_e32 v0, 6, v222
	s_nop 0
	v_add_u32_e32 v0, s0, v0
	s_mov_b32 s0, 0x8000
	v_cmp_gt_i32_e32 vcc, s0, v0
	s_and_saveexec_b64 s[0:1], vcc
	s_cbranch_execz .LBB0_1200
	v_readfirstlane_b32 s7, v0
	v_mbcnt_lo_u32_b32 v10, -1, 0
	v_mbcnt_hi_u32_b32 v10, -1, v10
	v_lshlrev_b32_e32 v2, 4, v10
	v_lshlrev_b32_e32 v3, 3, v10
	v_xor_b32_e32 v4, 32, v10
	v_lshlrev_b32_e32 v4, 2, v4
	v_xor_b32_e32 v5, 16, v10
	v_lshlrev_b32_e32 v5, 2, v5
	v_xor_b32_e32 v6, 8, v10
	v_lshlrev_b32_e32 v6, 2, v6
	v_xor_b32_e32 v7, 4, v10
	v_lshlrev_b32_e32 v7, 2, v7
	v_xor_b32_e32 v8, 2, v10
	v_lshlrev_b32_e32 v8, 2, v8
	v_xor_b32_e32 v9, 1, v10
	v_lshlrev_b32_e32 v9, 2, v9
	v_mov_b32_e32 v16, 0x358637bd
	v_readlane_b32 s22, v254, 12
	v_readlane_b32 s23, v254, 13
	v_readlane_b32 s24, v254, 55
	v_readlane_b32 s25, v254, 56
	v_readlane_b32 s20, v254, 14
	v_readlane_b32 s21, v254, 15
	s_add_u32 s18, s20, 0x123300
	s_addc_u32 s19, s21, 0
	s_nop 4
	global_load_dwordx4 v[136:139], v2, s[18:19] offset:0
	global_load_dwordx4 v[140:143], v2, s[18:19] offset:1024
	global_load_dwordx4 v[144:147], v2, s[18:19] offset:2048
	global_load_dwordx4 v[148:151], v2, s[18:19] offset:3072
	s_cmp_lt_u32 s7, 0x8000
	s_cselect_b32 s10, s22, s24
	s_cselect_b32 s11, s23, s25
	s_cselect_b32 s5, s7, 0x8000
	s_and_b32 s26, s7, 0x7fff
	s_lshl_b32 s27, s26, 12
	s_lshr_b32 s26, s26, 20
	s_add_u32 s10, s10, s27
	s_addc_u32 s11, s11, s26
	global_load_dwordx4 v[40:43], v2, s[10:11] offset:0
	global_load_dwordx4 v[44:47], v2, s[10:11] offset:1024
	global_load_dwordx4 v[48:51], v2, s[10:11] offset:2048
	global_load_dwordx4 v[52:55], v2, s[10:11] offset:3072
	s_waitcnt vmcnt(0)
.Lnf_loop:
	s_add_i32 s4, s7, s37
	s_cmp_lt_i32 s4, 0x8000
	s_cbranch_scc0 .Lnf_last0
	s_cmp_lt_u32 s4, 0x8000
	s_cselect_b32 s10, s22, s24
	s_cselect_b32 s11, s23, s25
	s_cselect_b32 s5, s4, 0x8000
	s_and_b32 s26, s4, 0x7fff
	s_lshl_b32 s27, s26, 12
	s_lshr_b32 s26, s26, 20
	s_add_u32 s10, s10, s27
	s_addc_u32 s11, s11, s26
	global_load_dwordx4 v[88:91], v2, s[10:11] offset:0
	global_load_dwordx4 v[92:95], v2, s[10:11] offset:1024
	global_load_dwordx4 v[96:99], v2, s[10:11] offset:2048
	global_load_dwordx4 v[100:103], v2, s[10:11] offset:3072
	v_mul_f32_e32 v12, v40, v40
	v_fmac_f32_e32 v12, v41, v41
	v_fmac_f32_e32 v12, v42, v42
	v_fmac_f32_e32 v12, v43, v43
	v_fmac_f32_e32 v12, v44, v44
	v_fmac_f32_e32 v12, v45, v45
	v_fmac_f32_e32 v12, v46, v46
	v_fmac_f32_e32 v12, v47, v47
	v_fmac_f32_e32 v12, v48, v48
	v_fmac_f32_e32 v12, v49, v49
	v_fmac_f32_e32 v12, v50, v50
	v_fmac_f32_e32 v12, v51, v51
	v_fmac_f32_e32 v12, v52, v52
	v_fmac_f32_e32 v12, v53, v53
	v_fmac_f32_e32 v12, v54, v54
	v_fmac_f32_e32 v12, v55, v55
	ds_bpermute_b32 v13, v4, v12
	s_waitcnt lgkmcnt(0)
	v_add_f32_e32 v12, v12, v13
	ds_bpermute_b32 v13, v5, v12
	s_waitcnt lgkmcnt(0)
	v_add_f32_e32 v12, v12, v13
	ds_bpermute_b32 v13, v6, v12
	s_waitcnt lgkmcnt(0)
	v_add_f32_e32 v12, v12, v13
	ds_bpermute_b32 v13, v7, v12
	s_waitcnt lgkmcnt(0)
	v_add_f32_e32 v12, v12, v13
	ds_bpermute_b32 v13, v8, v12
	s_waitcnt lgkmcnt(0)
	v_add_f32_e32 v12, v12, v13
	ds_bpermute_b32 v13, v9, v12
	s_waitcnt lgkmcnt(0)
	v_add_f32_e32 v12, v12, v13
	v_fmamk_f32 v12, v12, 0x3a800000, v16
	v_cmp_gt_f32_e32 vcc, 0x800000, v12
	v_mul_f32_e32 v13, 0x4b800000, v12
	s_nop 0
	v_cndmask_b32_e32 v12, v12, v13, vcc
	v_rsq_f32_e32 v12, v12
	s_nop 0
	v_mul_f32_e32 v13, 0x45800000, v12
	v_cndmask_b32_e32 v14, v12, v13, vcc
	s_lshl_b32 s12, s7, 12
	s_lshr_b32 s13, s7, 20
	s_add_u32 s12, s22, s12
	s_addc_u32 s13, s23, s13
	v_pk_mul_f32 v[40:41], v[40:41], v[14:15] op_sel_hi:[1,0]
	v_pk_mul_f32 v[40:41], v[136:137], v[40:41]
	v_pk_mul_f32 v[42:43], v[42:43], v[14:15] op_sel_hi:[1,0]
	v_pk_mul_f32 v[42:43], v[138:139], v[42:43]
	global_store_dwordx4 v2, v[40:43], s[12:13] offset:0
	v_pk_mul_f32 v[44:45], v[44:45], v[14:15] op_sel_hi:[1,0]
	v_pk_mul_f32 v[44:45], v[140:141], v[44:45]
	v_pk_mul_f32 v[46:47], v[46:47], v[14:15] op_sel_hi:[1,0]
	v_pk_mul_f32 v[46:47], v[142:143], v[46:47]
	global_store_dwordx4 v2, v[44:47], s[12:13] offset:1024
	v_pk_mul_f32 v[48:49], v[48:49], v[14:15] op_sel_hi:[1,0]
	v_pk_mul_f32 v[48:49], v[144:145], v[48:49]
	v_pk_mul_f32 v[50:51], v[50:51], v[14:15] op_sel_hi:[1,0]
	v_pk_mul_f32 v[50:51], v[146:147], v[50:51]
	global_store_dwordx4 v2, v[48:51], s[12:13] offset:2048
	v_pk_mul_f32 v[52:53], v[52:53], v[14:15] op_sel_hi:[1,0]
	v_pk_mul_f32 v[52:53], v[148:149], v[52:53]
	v_pk_mul_f32 v[54:55], v[54:55], v[14:15] op_sel_hi:[1,0]
	v_pk_mul_f32 v[54:55], v[150:151], v[54:55]
	global_store_dwordx4 v2, v[52:55], s[12:13] offset:3072
	s_waitcnt vmcnt(4)
	s_mov_b32 s7, s4
	s_add_i32 s4, s7, s37
	s_cmp_lt_i32 s4, 0x8000
	s_cbranch_scc0 .Lnf_last1
	s_cmp_lt_u32 s4, 0x8000
	s_cselect_b32 s10, s22, s24
	s_cselect_b32 s11, s23, s25
	s_cselect_b32 s5, s4, 0x8000
	s_and_b32 s26, s4, 0x7fff
	s_lshl_b32 s27, s26, 12
	s_lshr_b32 s26, s26, 20
	s_add_u32 s10, s10, s27
	s_addc_u32 s11, s11, s26
	global_load_dwordx4 v[40:43], v2, s[10:11] offset:0
	global_load_dwordx4 v[44:47], v2, s[10:11] offset:1024
	global_load_dwordx4 v[48:51], v2, s[10:11] offset:2048
	global_load_dwordx4 v[52:55], v2, s[10:11] offset:3072
	v_mul_f32_e32 v12, v88, v88
	v_fmac_f32_e32 v12, v89, v89
	v_fmac_f32_e32 v12, v90, v90
	v_fmac_f32_e32 v12, v91, v91
	v_fmac_f32_e32 v12, v92, v92
	v_fmac_f32_e32 v12, v93, v93
	v_fmac_f32_e32 v12, v94, v94
	v_fmac_f32_e32 v12, v95, v95
	v_fmac_f32_e32 v12, v96, v96
	v_fmac_f32_e32 v12, v97, v97
	v_fmac_f32_e32 v12, v98, v98
	v_fmac_f32_e32 v12, v99, v99
	v_fmac_f32_e32 v12, v100, v100
	v_fmac_f32_e32 v12, v101, v101
	v_fmac_f32_e32 v12, v102, v102
	v_fmac_f32_e32 v12, v103, v103
	ds_bpermute_b32 v13, v4, v12
	s_waitcnt lgkmcnt(0)
	v_add_f32_e32 v12, v12, v13
	ds_bpermute_b32 v13, v5, v12
	s_waitcnt lgkmcnt(0)
	v_add_f32_e32 v12, v12, v13
	ds_bpermute_b32 v13, v6, v12
	s_waitcnt lgkmcnt(0)
	v_add_f32_e32 v12, v12, v13
	ds_bpermute_b32 v13, v7, v12
	s_waitcnt lgkmcnt(0)
	v_add_f32_e32 v12, v12, v13
	ds_bpermute_b32 v13, v8, v12
	s_waitcnt lgkmcnt(0)
	v_add_f32_e32 v12, v12, v13
	ds_bpermute_b32 v13, v9, v12
	s_waitcnt lgkmcnt(0)
	v_add_f32_e32 v12, v12, v13
	v_fmamk_f32 v12, v12, 0x3a800000, v16
	v_cmp_gt_f32_e32 vcc, 0x800000, v12
	v_mul_f32_e32 v13, 0x4b800000, v12
	s_nop 0
	v_cndmask_b32_e32 v12, v12, v13, vcc
	v_rsq_f32_e32 v12, v12
	s_nop 0
	v_mul_f32_e32 v13, 0x45800000, v12
	v_cndmask_b32_e32 v14, v12, v13, vcc
	s_lshl_b32 s12, s7, 12
	s_lshr_b32 s13, s7, 20
	s_add_u32 s12, s22, s12
	s_addc_u32 s13, s23, s13
	v_pk_mul_f32 v[88:89], v[88:89], v[14:15] op_sel_hi:[1,0]
	v_pk_mul_f32 v[88:89], v[136:137], v[88:89]
	v_pk_mul_f32 v[90:91], v[90:91], v[14:15] op_sel_hi:[1,0]
	v_pk_mul_f32 v[90:91], v[138:139], v[90:91]
	global_store_dwordx4 v2, v[88:91], s[12:13] offset:0
	v_pk_mul_f32 v[92:93], v[92:93], v[14:15] op_sel_hi:[1,0]
	v_pk_mul_f32 v[92:93], v[140:141], v[92:93]
	v_pk_mul_f32 v[94:95], v[94:95], v[14:15] op_sel_hi:[1,0]
	v_pk_mul_f32 v[94:95], v[142:143], v[94:95]
	global_store_dwordx4 v2, v[92:95], s[12:13] offset:1024
	v_pk_mul_f32 v[96:97], v[96:97], v[14:15] op_sel_hi:[1,0]
	v_pk_mul_f32 v[96:97], v[144:145], v[96:97]
	v_pk_mul_f32 v[98:99], v[98:99], v[14:15] op_sel_hi:[1,0]
	v_pk_mul_f32 v[98:99], v[146:147], v[98:99]
	global_store_dwordx4 v2, v[96:99], s[12:13] offset:2048
	v_pk_mul_f32 v[100:101], v[100:101], v[14:15] op_sel_hi:[1,0]
	v_pk_mul_f32 v[100:101], v[148:149], v[100:101]
	v_pk_mul_f32 v[102:103], v[102:103], v[14:15] op_sel_hi:[1,0]
	v_pk_mul_f32 v[102:103], v[150:151], v[102:103]
	global_store_dwordx4 v2, v[100:103], s[12:13] offset:3072
	s_waitcnt vmcnt(4)
	s_mov_b32 s7, s4
	s_branch .Lnf_loop
.Lnf_last0:
	v_mul_f32_e32 v12, v40, v40
	v_fmac_f32_e32 v12, v41, v41
	v_fmac_f32_e32 v12, v42, v42
	v_fmac_f32_e32 v12, v43, v43
	v_fmac_f32_e32 v12, v44, v44
	v_fmac_f32_e32 v12, v45, v45
	v_fmac_f32_e32 v12, v46, v46
	v_fmac_f32_e32 v12, v47, v47
	v_fmac_f32_e32 v12, v48, v48
	v_fmac_f32_e32 v12, v49, v49
	v_fmac_f32_e32 v12, v50, v50
	v_fmac_f32_e32 v12, v51, v51
	v_fmac_f32_e32 v12, v52, v52
	v_fmac_f32_e32 v12, v53, v53
	v_fmac_f32_e32 v12, v54, v54
	v_fmac_f32_e32 v12, v55, v55
	ds_bpermute_b32 v13, v4, v12
	s_waitcnt lgkmcnt(0)
	v_add_f32_e32 v12, v12, v13
	ds_bpermute_b32 v13, v5, v12
	s_waitcnt lgkmcnt(0)
	v_add_f32_e32 v12, v12, v13
	ds_bpermute_b32 v13, v6, v12
	s_waitcnt lgkmcnt(0)
	v_add_f32_e32 v12, v12, v13
	ds_bpermute_b32 v13, v7, v12
	s_waitcnt lgkmcnt(0)
	v_add_f32_e32 v12, v12, v13
	ds_bpermute_b32 v13, v8, v12
	s_waitcnt lgkmcnt(0)
	v_add_f32_e32 v12, v12, v13
	ds_bpermute_b32 v13, v9, v12
	s_waitcnt lgkmcnt(0)
	v_add_f32_e32 v12, v12, v13
	v_fmamk_f32 v12, v12, 0x3a800000, v16
	v_cmp_gt_f32_e32 vcc, 0x800000, v12
	v_mul_f32_e32 v13, 0x4b800000, v12
	s_nop 0
	v_cndmask_b32_e32 v12, v12, v13, vcc
	v_rsq_f32_e32 v12, v12
	s_nop 0
	v_mul_f32_e32 v13, 0x45800000, v12
	v_cndmask_b32_e32 v14, v12, v13, vcc
	s_lshl_b32 s12, s7, 12
	s_lshr_b32 s13, s7, 20
	s_add_u32 s12, s22, s12
	s_addc_u32 s13, s23, s13
	v_pk_mul_f32 v[40:41], v[40:41], v[14:15] op_sel_hi:[1,0]
	v_pk_mul_f32 v[40:41], v[136:137], v[40:41]
	v_pk_mul_f32 v[42:43], v[42:43], v[14:15] op_sel_hi:[1,0]
	v_pk_mul_f32 v[42:43], v[138:139], v[42:43]
	global_store_dwordx4 v2, v[40:43], s[12:13] offset:0
	v_pk_mul_f32 v[44:45], v[44:45], v[14:15] op_sel_hi:[1,0]
	v_pk_mul_f32 v[44:45], v[140:141], v[44:45]
	v_pk_mul_f32 v[46:47], v[46:47], v[14:15] op_sel_hi:[1,0]
	v_pk_mul_f32 v[46:47], v[142:143], v[46:47]
	global_store_dwordx4 v2, v[44:47], s[12:13] offset:1024
	v_pk_mul_f32 v[48:49], v[48:49], v[14:15] op_sel_hi:[1,0]
	v_pk_mul_f32 v[48:49], v[144:145], v[48:49]
	v_pk_mul_f32 v[50:51], v[50:51], v[14:15] op_sel_hi:[1,0]
	v_pk_mul_f32 v[50:51], v[146:147], v[50:51]
	global_store_dwordx4 v2, v[48:51], s[12:13] offset:2048
	v_pk_mul_f32 v[52:53], v[52:53], v[14:15] op_sel_hi:[1,0]
	v_pk_mul_f32 v[52:53], v[148:149], v[52:53]
	v_pk_mul_f32 v[54:55], v[54:55], v[14:15] op_sel_hi:[1,0]
	v_pk_mul_f32 v[54:55], v[150:151], v[54:55]
	global_store_dwordx4 v2, v[52:55], s[12:13] offset:3072
	s_branch .Lnf_done
.Lnf_last1:
	v_mul_f32_e32 v12, v88, v88
	v_fmac_f32_e32 v12, v89, v89
	v_fmac_f32_e32 v12, v90, v90
	v_fmac_f32_e32 v12, v91, v91
	v_fmac_f32_e32 v12, v92, v92
	v_fmac_f32_e32 v12, v93, v93
	v_fmac_f32_e32 v12, v94, v94
	v_fmac_f32_e32 v12, v95, v95
	v_fmac_f32_e32 v12, v96, v96
	v_fmac_f32_e32 v12, v97, v97
	v_fmac_f32_e32 v12, v98, v98
	v_fmac_f32_e32 v12, v99, v99
	v_fmac_f32_e32 v12, v100, v100
	v_fmac_f32_e32 v12, v101, v101
	v_fmac_f32_e32 v12, v102, v102
	v_fmac_f32_e32 v12, v103, v103
	ds_bpermute_b32 v13, v4, v12
	s_waitcnt lgkmcnt(0)
	v_add_f32_e32 v12, v12, v13
	ds_bpermute_b32 v13, v5, v12
	s_waitcnt lgkmcnt(0)
	v_add_f32_e32 v12, v12, v13
	ds_bpermute_b32 v13, v6, v12
	s_waitcnt lgkmcnt(0)
	v_add_f32_e32 v12, v12, v13
	ds_bpermute_b32 v13, v7, v12
	s_waitcnt lgkmcnt(0)
	v_add_f32_e32 v12, v12, v13
	ds_bpermute_b32 v13, v8, v12
	s_waitcnt lgkmcnt(0)
	v_add_f32_e32 v12, v12, v13
	ds_bpermute_b32 v13, v9, v12
	s_waitcnt lgkmcnt(0)
	v_add_f32_e32 v12, v12, v13
	v_fmamk_f32 v12, v12, 0x3a800000, v16
	v_cmp_gt_f32_e32 vcc, 0x800000, v12
	v_mul_f32_e32 v13, 0x4b800000, v12
	s_nop 0
	v_cndmask_b32_e32 v12, v12, v13, vcc
	v_rsq_f32_e32 v12, v12
	s_nop 0
	v_mul_f32_e32 v13, 0x45800000, v12
	v_cndmask_b32_e32 v14, v12, v13, vcc
	s_lshl_b32 s12, s7, 12
	s_lshr_b32 s13, s7, 20
	s_add_u32 s12, s22, s12
	s_addc_u32 s13, s23, s13
	v_pk_mul_f32 v[88:89], v[88:89], v[14:15] op_sel_hi:[1,0]
	v_pk_mul_f32 v[88:89], v[136:137], v[88:89]
	v_pk_mul_f32 v[90:91], v[90:91], v[14:15] op_sel_hi:[1,0]
	v_pk_mul_f32 v[90:91], v[138:139], v[90:91]
	global_store_dwordx4 v2, v[88:91], s[12:13] offset:0
	v_pk_mul_f32 v[92:93], v[92:93], v[14:15] op_sel_hi:[1,0]
	v_pk_mul_f32 v[92:93], v[140:141], v[92:93]
	v_pk_mul_f32 v[94:95], v[94:95], v[14:15] op_sel_hi:[1,0]
	v_pk_mul_f32 v[94:95], v[142:143], v[94:95]
	global_store_dwordx4 v2, v[92:95], s[12:13] offset:1024
	v_pk_mul_f32 v[96:97], v[96:97], v[14:15] op_sel_hi:[1,0]
	v_pk_mul_f32 v[96:97], v[144:145], v[96:97]
	v_pk_mul_f32 v[98:99], v[98:99], v[14:15] op_sel_hi:[1,0]
	v_pk_mul_f32 v[98:99], v[146:147], v[98:99]
	global_store_dwordx4 v2, v[96:99], s[12:13] offset:2048
	v_pk_mul_f32 v[100:101], v[100:101], v[14:15] op_sel_hi:[1,0]
	v_pk_mul_f32 v[100:101], v[148:149], v[100:101]
	v_pk_mul_f32 v[102:103], v[102:103], v[14:15] op_sel_hi:[1,0]
	v_pk_mul_f32 v[102:103], v[150:151], v[102:103]
	global_store_dwordx4 v2, v[100:103], s[12:13] offset:3072
.Lnf_done:
	s_branch .LBB0_1200
.LBB0_1200:
	s_endpgm
